# GEMM run prologue: the second K-tile's 6 stage loads issued together with the first tile's 8 (first wait vmcnt(2)->vmcnt(8) after all 14), saving one exposed cold latency per phase; on top of v038
# speedup vs baseline: 1.0142x; 1.0053x over previous
.LBB0_774:
	v_mov_b32_e32 v199, v3
	v_mov_b32_e32 v203, v3
	s_cmp_lt_i32 s67, s7
	v_lshl_add_u64 v[8:9], s[0:1], 0, v[198:199]
	v_lshl_add_u64 v[10:11], s[0:1], 0, v[202:203]
	s_cselect_b64 s[0:1], -1, 0
	v_lshl_add_u64 v[4:5], s[52:53], 0, v[198:199]
	s_cmp_lg_u64 s[0:1], 0
	v_lshl_add_u64 v[6:7], s[52:53], 0, v[202:203]
	v_mov_b32_e32 v197, v3
	s_addc_u32 s0, s6, 0
	v_lshl_add_u64 v[4:5], v[4:5], 0, s[60:61]
	s_add_i32 m0, s78, 0x18000
	v_lshl_add_u64 v[12:13], s[90:91], 0, v[196:197]
	v_mov_b32_e32 v201, v3
	global_load_lds_dwordx4 v[4:5], off
	v_lshl_add_u64 v[4:5], v[6:7], 0, s[60:61]
	s_add_i32 m0, s78, 0x1a000
	s_add_i32 s35, s78, 0x8000
	v_lshl_add_u64 v[14:15], s[90:91], 0, v[200:201]
	global_load_lds_dwordx4 v[4:5], off
	v_lshl_add_u64 v[4:5], v[12:13], 0, s[60:61]
	s_mov_b32 m0, s35
	s_add_i32 s46, s78, 0xa000
	global_load_lds_dwordx4 v[4:5], off
	v_lshl_add_u64 v[4:5], v[14:15], 0, s[60:61]
	s_mov_b32 m0, s46
	v_mov_b32_e32 v2, v3
	global_load_lds_dwordx4 v[4:5], off
	v_lshl_add_u64 v[4:5], v[8:9], 0, s[60:61]
	s_add_i32 m0, s78, 0x1c000
	s_lshl_b32 s47, s0, 1
	global_load_lds_dwordx4 v[4:5], off
	v_lshl_add_u64 v[4:5], v[10:11], 0, s[60:61]
	s_add_i32 m0, s78, 0x1e000
	s_nop 0
	global_load_lds_dwordx4 v[4:5], off
	s_waitcnt vmcnt(8)
	s_barrier
	s_waitcnt vmcnt(6)
	v_mov_b32_e32 v4, v3
	v_mov_b32_e32 v5, v3
	v_mov_b64_e32 v[12:13], v[4:5]
	v_mov_b64_e32 v[8:9], v[4:5]
	v_mov_b64_e32 v[20:21], v[4:5]
	v_mov_b64_e32 v[16:17], v[4:5]
	v_mov_b64_e32 v[28:29], v[4:5]
	v_mov_b64_e32 v[24:25], v[4:5]
	v_mov_b64_e32 v[36:37], v[4:5]
	v_mov_b64_e32 v[32:33], v[4:5]
	v_mov_b64_e32 v[44:45], v[4:5]
	v_mov_b64_e32 v[40:41], v[4:5]
	v_mov_b64_e32 v[52:53], v[4:5]
	v_mov_b64_e32 v[48:49], v[4:5]
	v_mov_b64_e32 v[76:77], v[4:5]
	v_mov_b64_e32 v[72:73], v[4:5]
	v_mov_b64_e32 v[84:85], v[4:5]
	v_mov_b64_e32 v[80:81], v[4:5]
	v_mov_b64_e32 v[92:93], v[4:5]
	v_mov_b64_e32 v[88:89], v[4:5]
	v_mov_b64_e32 v[100:101], v[4:5]
	v_mov_b64_e32 v[96:97], v[4:5]
	v_mov_b64_e32 v[108:109], v[4:5]
	v_mov_b64_e32 v[104:105], v[4:5]
	v_mov_b64_e32 v[116:117], v[4:5]
	v_mov_b64_e32 v[112:113], v[4:5]
	v_mov_b64_e32 v[124:125], v[4:5]
	v_mov_b64_e32 v[120:121], v[4:5]
	v_mov_b64_e32 v[132:133], v[4:5]
	v_mov_b64_e32 v[128:129], v[4:5]
	v_mov_b64_e32 v[56:57], v[4:5]
	v_mov_b64_e32 v[64:65], v[4:5]
	v_mov_b64_e32 v[60:61], v[4:5]
	v_mov_b64_e32 v[68:69], v[4:5]
	v_mov_b64_e32 v[10:11], v[2:3]
	v_mov_b64_e32 v[6:7], v[2:3]
	v_mov_b64_e32 v[18:19], v[2:3]
	v_mov_b64_e32 v[14:15], v[2:3]
	v_mov_b64_e32 v[26:27], v[2:3]
	v_mov_b64_e32 v[22:23], v[2:3]
	v_mov_b64_e32 v[34:35], v[2:3]
	v_mov_b64_e32 v[30:31], v[2:3]
	v_mov_b64_e32 v[42:43], v[2:3]
	v_mov_b64_e32 v[38:39], v[2:3]
	v_mov_b64_e32 v[50:51], v[2:3]
	v_mov_b64_e32 v[46:47], v[2:3]
	v_mov_b64_e32 v[74:75], v[2:3]
	v_mov_b64_e32 v[70:71], v[2:3]
	v_mov_b64_e32 v[82:83], v[2:3]
	v_mov_b64_e32 v[78:79], v[2:3]
	v_mov_b64_e32 v[90:91], v[2:3]
	v_mov_b64_e32 v[86:87], v[2:3]
	v_mov_b64_e32 v[98:99], v[2:3]
	v_mov_b64_e32 v[94:95], v[2:3]
	v_mov_b64_e32 v[106:107], v[2:3]
	v_mov_b64_e32 v[102:103], v[2:3]
	v_mov_b64_e32 v[114:115], v[2:3]
	v_mov_b64_e32 v[110:111], v[2:3]
	v_mov_b64_e32 v[122:123], v[2:3]
	v_mov_b64_e32 v[118:119], v[2:3]
	v_mov_b64_e32 v[130:131], v[2:3]
	v_mov_b64_e32 v[126:127], v[2:3]
	v_mov_b64_e32 v[54:55], v[2:3]
	v_mov_b64_e32 v[62:63], v[2:3]
	v_mov_b64_e32 v[58:59], v[2:3]
	v_mov_b64_e32 v[66:67], v[2:3]
	s_barrier
	s_branch .LBB0_777
